# DSA indexer: key-tile loads prefetched three tiles ahead (4 rotating register sets, scalar loop control)
# speedup vs baseline: 1.0441x; 1.0019x over previous
; DI float bflo(unsigned v) { return __uint_as_float(v << 16); }
; DI float bfhi(unsigned v) { return __uint_as_float(v & 0xffff0000u); }
; DI void dsa_item(const Params& P0_, int b, int item, uchar* smem) {
;     ...
;     const int hidx = (r31 & 3) | (((r31 >> 3) & 1) << 2), ql = ((r31 >> 2) & 1) | (((r31 >> 4) & 1) << 1);
;     bf16x8 af[4];
;     const u16* arow = H + (tokbase + q0 + ql) * HC + A_QI + hidx * 64;
; #pragma unroll
;     for (int s = 0; s < 4; ++s) af[s] = *(const bf16x8*)(arow + 16 * s + 8 * h);
;     float wa[8], wb[8];
;     { const uint4 va = *(const uint4*)(H + (tokbase + q0 + h) * HC + A_W), vb = *(const uint4*)(H + (tokbase + q0 + h + 2) * HC + A_W);
;       wa[0] = bflo(va.x); wa[1] = bfhi(va.x); wa[2] = bflo(va.y); wa[3] = bfhi(va.y); wa[4] = bflo(va.z); wa[5] = bfhi(va.z); wa[6] = bflo(va.w); wa[7] = bfhi(va.w);
;       wb[0] = bflo(vb.x); wb[1] = bfhi(vb.x); wb[2] = bflo(vb.y); wb[3] = bfhi(vb.y); wb[4] = bflo(vb.z); wb[5] = bfhi(vb.z); wb[6] = bflo(vb.w); wb[7] = bfhi(vb.w); }
;     const int nkt = (q0 + 3) / 32 + 1;
;     const u16* KIF = (const u16*)(P.ws() + OFF_KIF);
;     bf16x8 k0f, k1f, k2f, k3f;
;     {
;       const int c0 = wave < nkt ? wave : 0;
;       const u16* krow = KIF + ((size_t)((tokbase >> 5) + c0) * 256 + lane) * 8;
;       k0f = *(const bf16x8*)(krow); k1f = *(const bf16x8*)(krow + 512); k2f = *(const bf16x8*)(krow + 1024); k3f = *(const bf16x8*)(krow + 1536);
;     }
;     for (int c = wave; c < nkt; c += 4) {
;       bf16x8 n0f = k0f, n1f = k1f, n2f = k2f, n3f = k3f;
;       if (c + 4 < nkt) {
;         const u16* krow = KIF + ((size_t)((tokbase >> 5) + c + 4) * 256 + lane) * 8;
;         n0f = *(const bf16x8*)(krow); n1f = *(const bf16x8*)(krow + 512); n2f = *(const bf16x8*)(krow + 1024); n3f = *(const bf16x8*)(krow + 1536);
;       }
.LBB0_258:
	s_cmp_lt_i32 s6, 0
	s_cbranch_scc1 .LBB0_400
	v_readlane_b32 s0, v253, 32
	v_readlane_b32 s1, v253, 33
	s_load_dwordx2 s[0:1], s[0:1], 0xe8
	s_waitcnt vmcnt(62)
	v_mov_b32_e32 v6, v166
	s_waitcnt vmcnt(33) lgkmcnt(0)
	v_ashrrev_i32_e32 v64, 6, v6
	v_writelane_b32 v253, s0, 63
	v_and_b32_e32 v62, 63, v6
	s_barrier
	v_writelane_b32 v254, s1, 0
	s_lshl_b32 s0, s6, 2
	s_sub_i32 s12, 0xffc, s0
	s_sub_i32 s0, 0xfff, s0
	s_ashr_i32 s1, s0, 31
	v_readlane_b32 s6, v253, 57
	s_lshr_b32 s1, s1, 27
	v_readlane_b32 s7, v253, 58
	s_lshl_b32 s6, s71, 12
	s_add_i32 s0, s0, s1
	v_writelane_b32 v253, s6, 57
	s_ashr_i32 s13, s0, 5
	v_cmp_ge_i32_e32 vcc, s13, v64
	v_writelane_b32 v253, s7, 58
	s_and_saveexec_b64 s[6:7], vcc
	s_cbranch_execz .LBB0_271
	v_readlane_b32 s16, v253, 63
	v_readlane_b32 s17, v254, 0
	s_add_u32 s0, s16, 0x6100000
	s_addc_u32 s1, s17, 0
	s_ashr_i32 s8, s12, 31
	v_readlane_b32 s14, v253, 57
	v_lshrrev_b32_e32 v7, 5, v62
	s_add_u32 s9, s12, s14
	v_or_b32_e32 v0, s9, v7
	v_mov_b64_e32 v[2:3], s[0:1]
	v_mad_u64_u32 v[4:5], s[0:1], v0, s33, v[2:3]
	s_addc_u32 s10, s8, 0
	s_movk_i32 s0, 0x1000
	v_mad_i32_i24 v0, s10, v228, v5
	v_add_co_u32_e32 v8, vcc, s0, v4
	s_movk_i32 s0, 0x5000
	s_nop 0
	v_addc_co_u32_e32 v9, vcc, 0, v0, vcc
	v_add_co_u32_e32 v4, vcc, s0, v4
	v_readlane_b32 s15, v253, 58
	s_nop 0
	v_addc_co_u32_e32 v5, vcc, 0, v0, vcc
	global_load_dwordx4 v[8:11], v[8:9], off offset:2944
	s_nop 0
	global_load_dwordx4 v[12:15], v[4:5], off offset:896
	v_lshrrev_b32_e32 v4, 3, v6
	v_bfe_u32 v0, v6, 2, 1
	v_and_b32_e32 v4, 2, v4
	v_or3_b32 v0, v0, v4, s9
	v_mad_u64_u32 v[2:3], s[8:9], v0, s33, v[2:3]
	v_lshrrev_b32_e32 v0, 1, v6
	v_and_b32_e32 v4, 3, v6
	v_and_or_b32 v0, v0, 4, v4
	v_mad_i32_i24 v3, s10, v228, v3
	v_lshlrev_b32_e32 v0, 7, v0
	s_lshr_b32 s0, s14, 5
	s_mov_b32 s1, s15
	v_lshl_add_u64 v[2:3], v[2:3], 0, v[0:1]
	v_lshlrev_b32_e32 v0, 4, v7
	v_ashrrev_i32_e32 v65, 31, v64
	v_lshl_add_u64 v[16:17], v[2:3], 0, v[0:1]
	v_lshl_add_u64 v[2:3], s[0:1], 0, v[64:65]
	v_lshlrev_b64 v[34:35], 12, v[2:3]
	v_lshl_add_u64 v[2:3], s[16:17], 0, v[34:35]
	v_lshlrev_b32_e32 v0, 4, v62
	v_lshl_add_u64 v[2:3], v[2:3], 0, v[0:1]
	s_mov_b64 s[0:1], 0x1bfa3e00
	v_lshl_add_u64 v[4:5], v[2:3], 0, s[0:1]
	global_load_dwordx4 v[18:21], v[16:17], off offset:1632
	global_load_dwordx4 v[22:25], v[16:17], off offset:1600
	global_load_dwordx4 v[50:53], v[4:5], off offset:3072
	global_load_dwordx4 v[54:57], v[4:5], off offset:2048
	global_load_dwordx4 v[58:61], v[4:5], off offset:1024
	v_add_co_u32_e32 v2, vcc, 0x1bfa3000, v2
	v_and_b32_e32 v6, 31, v6
	s_nop 0
	v_addc_co_u32_e32 v3, vcc, 0, v3, vcc
	global_load_dwordx4 v[84:87], v[2:3], off offset:3584
	s_nop 0
	global_load_dwordx4 v[26:29], v[16:17], off offset:1568
	global_load_dwordx4 v[30:33], v[16:17], off offset:1536
	v_lshlrev_b32_e32 v16, 7, v64
	v_lshl_add_u32 v7, v7, 14, v16
	v_or_b32_e32 v34, v34, v0
	v_lshl_or_b32 v65, v6, 2, v7
	v_lshl_add_u64 v[6:7], s[16:17], 0, v[34:35]
	s_mov_b64 s[0:1], 0x1bfa8600
	s_mov_b64 s[8:9], 0
	v_mov_b32_e32 v63, v64
	s_waitcnt vmcnt(42)
	v_lshl_add_u64 v[66:67], v[6:7], 0, s[0:1]
	s_waitcnt vmcnt(9)
	v_lshlrev_b32_e32 v0, 16, v8
	v_and_b32_e32 v68, 0xffff0000, v8
	v_lshlrev_b32_e32 v69, 16, v9
	v_and_b32_e32 v70, 0xffff0000, v9
	v_lshlrev_b32_e32 v71, 16, v10
	v_and_b32_e32 v72, 0xffff0000, v10
	v_lshlrev_b32_e32 v73, 16, v11
	v_and_b32_e32 v74, 0xffff0000, v11
	s_waitcnt vmcnt(8)
	v_lshlrev_b32_e32 v75, 16, v12
	v_and_b32_e32 v76, 0xffff0000, v12
	v_lshlrev_b32_e32 v77, 16, v13
	v_and_b32_e32 v78, 0xffff0000, v13
	v_lshlrev_b32_e32 v79, 16, v14
	v_and_b32_e32 v80, 0xffff0000, v14
	v_lshlrev_b32_e32 v81, 16, v15
	v_and_b32_e32 v82, 0xffff0000, v15
	v_readfirstlane_b32 s32, v64
	s_add_i32 s100, s32, 4
	s_cmp_le_i32 s100, s13
	s_cbranch_scc0 .Lix_p1
	global_load_dwordx4 v[46:49], v[66:67], off offset:-2048
	global_load_dwordx4 v[42:45], v[66:67], off offset:-1024
	global_load_dwordx4 v[38:41], v[66:67], off
	global_load_dwordx4 v[34:37], v[66:67], off offset:1024
.Lix_p1:
	s_mov_b64 s[0:1], 0x4000
	v_lshl_add_u64 v[66:67], v[66:67], 0, s[0:1]
	s_add_i32 s100, s32, 8
	s_cmp_le_i32 s100, s13
	s_cbranch_scc0 .Lix_p2
	global_load_dwordx4 v[100:103], v[66:67], off offset:-2048
	global_load_dwordx4 v[96:99], v[66:67], off offset:-1024
	global_load_dwordx4 v[92:95], v[66:67], off
	global_load_dwordx4 v[88:91], v[66:67], off offset:1024
.Lix_p2:
	v_lshl_add_u64 v[66:67], v[66:67], 0, s[0:1]
	s_branch .Lix_v0

; DI f32x16 mfma32(bf16x8 a, bf16x8 b, f32x16 c) { return __builtin_amdgcn_mfma_f32_32x32x16_bf16(a, b, c, 0, 0, 0); }
; DI f32x16 zero16() { f32x16 z; for (int i = 0; i < 16; ++i) z[i] = 0.f; return z; }
; DI void dsa_item(const Params& P0_, int b, int item, uchar* smem) {
;     ...
;     for (int c = wave; c < nkt; c += 4) {
;       bf16x8 n0f = k0f, n1f = k1f, n2f = k2f, n3f = k3f;
;       if (c + 4 < nkt) {
;         const u16* krow = KIF + ((size_t)((tokbase >> 5) + c + 4) * 256 + lane) * 8;
;         n0f = *(const bf16x8*)(krow); n1f = *(const bf16x8*)(krow + 512); n2f = *(const bf16x8*)(krow + 1024); n3f = *(const bf16x8*)(krow + 1536);
;       }
;       f32x16 a = zero16();
;       a = mfma32(af[0], k0f, a); a = mfma32(af[1], k1f, a); a = mfma32(af[2], k2f, a); a = mfma32(af[3], k3f, a);
;       float sa = 0.f, sb = 0.f;
; #pragma unroll
;       for (int i = 0; i < 8; ++i) { sa += fmaxf(a[i], 0.f) * wa[i]; sb += fmaxf(a[8 + i], 0.f) * wb[i]; }
;       sc[h * 4096 + 32 * c + r31] = sa;
;       sc[(h + 2) * 4096 + 32 * c + r31] = sb;
;       k0f = n0f; k1f = n1f; k2f = n2f; k3f = n3f;
;     }
.Lix_v0:
	s_add_i32 s100, s32, 12
	s_cmp_le_i32 s100, s13
	s_cbranch_scc0 .Lix_ni0
	global_load_dwordx4 v[116:119], v[66:67], off offset:-2048
	global_load_dwordx4 v[112:115], v[66:67], off offset:-1024
	global_load_dwordx4 v[108:111], v[66:67], off
	global_load_dwordx4 v[104:107], v[66:67], off offset:1024
.Lix_ni0:
	s_mov_b64 s[0:1], 0x4000
	v_lshl_add_u64 v[66:67], v[66:67], 0, s[0:1]
	s_sub_i32 s100, s13, s32
	s_cmp_ge_i32 s100, 12
	s_cbranch_scc1 .Lix_w12_0
	s_cmp_ge_i32 s100, 8
	s_cbranch_scc1 .Lix_w8_0
	s_cmp_ge_i32 s100, 4
	s_cbranch_scc1 .Lix_w4_0
	s_waitcnt vmcnt(0)
	s_branch .Lix_go0
.Lix_w12_0:
	s_waitcnt vmcnt(12)
	s_branch .Lix_go0
.Lix_w8_0:
	s_waitcnt vmcnt(8)
	s_branch .Lix_go0
.Lix_w4_0:
	s_waitcnt vmcnt(4)
.Lix_go0:
	v_mfma_f32_32x32x16_bf16 v[2:17], v[30:33], v[84:87], 0
	v_mfma_f32_32x32x16_bf16 v[2:17], v[26:29], v[58:61], v[2:17]
	v_mfma_f32_32x32x16_bf16 v[2:17], v[22:25], v[54:57], v[2:17]
	v_mfma_f32_32x32x16_bf16 v[2:17], v[18:21], v[50:53], v[2:17]
	s_nop 11
	v_max_f32_e32 v10, 0, v10
	v_max_f32_e32 v2, 0, v2
	v_max_f32_e32 v11, 0, v11
	v_fma_f32 v10, v10, v75, 0
	v_max_f32_e32 v3, 0, v3
	v_max_f32_e32 v12, 0, v12
	v_fma_f32 v2, v2, v0, 0
	v_fmac_f32_e32 v10, v11, v76
	v_max_f32_e32 v4, 0, v4
	v_max_f32_e32 v13, 0, v13
	v_fmac_f32_e32 v2, v3, v68
	v_fmac_f32_e32 v10, v12, v77
	v_max_f32_e32 v5, 0, v5
	v_max_f32_e32 v14, 0, v14
	v_fmac_f32_e32 v2, v4, v69
	v_fmac_f32_e32 v10, v13, v78
	v_max_f32_e32 v6, 0, v6
	v_fmac_f32_e32 v2, v5, v70
	v_fmac_f32_e32 v10, v14, v79
	v_max_f32_e32 v3, 0, v15
	v_max_f32_e32 v7, 0, v7
	v_fmac_f32_e32 v2, v6, v71
	v_fmac_f32_e32 v10, v3, v80
	v_fmac_f32_e32 v2, v7, v72
	v_max_f32_e32 v3, 0, v8
	v_fmac_f32_e32 v2, v3, v73
	v_max_f32_e32 v3, 0, v16
	v_fmac_f32_e32 v10, v3, v81
	v_max_f32_e32 v3, 0, v9
	v_fmac_f32_e32 v2, v3, v74
	v_max_f32_e32 v3, 0, v17
	v_fmac_f32_e32 v10, v3, v82
	ds_write2st64_b32 v65, v2, v10 offset1:128
	v_add_u32_e32 v65, 0x200, v65
	s_add_i32 s32, s32, 4
	s_cmp_gt_i32 s32, s13
	s_cbranch_scc1 .LBB0_271
.Lix_v1:
	s_add_i32 s100, s32, 12
	s_cmp_le_i32 s100, s13
	s_cbranch_scc0 .Lix_ni1
	global_load_dwordx4 v[84:87], v[66:67], off offset:-2048
	global_load_dwordx4 v[58:61], v[66:67], off offset:-1024
	global_load_dwordx4 v[54:57], v[66:67], off
	global_load_dwordx4 v[50:53], v[66:67], off offset:1024

; DI f32x16 mfma32(bf16x8 a, bf16x8 b, f32x16 c) { return __builtin_amdgcn_mfma_f32_32x32x16_bf16(a, b, c, 0, 0, 0); }
; DI f32x16 zero16() { f32x16 z; for (int i = 0; i < 16; ++i) z[i] = 0.f; return z; }
; DI void dsa_item(const Params& P0_, int b, int item, uchar* smem) {
;     ...
;     for (int c = wave; c < nkt; c += 4) {
;       bf16x8 n0f = k0f, n1f = k1f, n2f = k2f, n3f = k3f;
;       if (c + 4 < nkt) {
;         const u16* krow = KIF + ((size_t)((tokbase >> 5) + c + 4) * 256 + lane) * 8;
;         n0f = *(const bf16x8*)(krow); n1f = *(const bf16x8*)(krow + 512); n2f = *(const bf16x8*)(krow + 1024); n3f = *(const bf16x8*)(krow + 1536);
;       }
;       f32x16 a = zero16();
;       a = mfma32(af[0], k0f, a); a = mfma32(af[1], k1f, a); a = mfma32(af[2], k2f, a); a = mfma32(af[3], k3f, a);
;       float sa = 0.f, sb = 0.f;
; #pragma unroll
;       for (int i = 0; i < 8; ++i) { sa += fmaxf(a[i], 0.f) * wa[i]; sb += fmaxf(a[8 + i], 0.f) * wb[i]; }
;       sc[h * 4096 + 32 * c + r31] = sa;
;       sc[(h + 2) * 4096 + 32 * c + r31] = sb;
;       k0f = n0f; k1f = n1f; k2f = n2f; k3f = n3f;
;     }
.Lix_go1:
	v_mfma_f32_32x32x16_bf16 v[2:17], v[30:33], v[46:49], 0
	v_mfma_f32_32x32x16_bf16 v[2:17], v[26:29], v[42:45], v[2:17]
	v_mfma_f32_32x32x16_bf16 v[2:17], v[22:25], v[38:41], v[2:17]
	v_mfma_f32_32x32x16_bf16 v[2:17], v[18:21], v[34:37], v[2:17]
	s_nop 11
	v_max_f32_e32 v10, 0, v10
	v_max_f32_e32 v2, 0, v2
	v_max_f32_e32 v11, 0, v11
	v_fma_f32 v10, v10, v75, 0
	v_max_f32_e32 v3, 0, v3
	v_max_f32_e32 v12, 0, v12
	v_fma_f32 v2, v2, v0, 0
	v_fmac_f32_e32 v10, v11, v76
	v_max_f32_e32 v4, 0, v4
	v_max_f32_e32 v13, 0, v13
	v_fmac_f32_e32 v2, v3, v68
	v_fmac_f32_e32 v10, v12, v77
	v_max_f32_e32 v5, 0, v5
	v_max_f32_e32 v14, 0, v14
	v_fmac_f32_e32 v2, v4, v69
	v_fmac_f32_e32 v10, v13, v78
	v_max_f32_e32 v6, 0, v6
	v_fmac_f32_e32 v2, v5, v70
	v_fmac_f32_e32 v10, v14, v79
	v_max_f32_e32 v3, 0, v15
	v_max_f32_e32 v7, 0, v7
	v_fmac_f32_e32 v2, v6, v71
	v_fmac_f32_e32 v10, v3, v80
	v_fmac_f32_e32 v2, v7, v72
	v_max_f32_e32 v3, 0, v8
	v_fmac_f32_e32 v2, v3, v73
	v_max_f32_e32 v3, 0, v16
	v_fmac_f32_e32 v10, v3, v81
	v_max_f32_e32 v3, 0, v9
	v_fmac_f32_e32 v2, v3, v74
	v_max_f32_e32 v3, 0, v17
	v_fmac_f32_e32 v10, v3, v82
	ds_write2st64_b32 v65, v2, v10 offset1:128
	v_add_u32_e32 v65, 0x200, v65
	s_add_i32 s32, s32, 4
	s_cmp_gt_i32 s32, s13
	s_cbranch_scc1 .LBB0_271
.Lix_v2:
	s_add_i32 s100, s32, 12
	s_cmp_le_i32 s100, s13
	s_cbranch_scc0 .Lix_ni2
	global_load_dwordx4 v[46:49], v[66:67], off offset:-2048
	global_load_dwordx4 v[42:45], v[66:67], off offset:-1024
	global_load_dwordx4 v[38:41], v[66:67], off
	global_load_dwordx4 v[34:37], v[66:67], off offset:1024

; DI f32x16 mfma32(bf16x8 a, bf16x8 b, f32x16 c) { return __builtin_amdgcn_mfma_f32_32x32x16_bf16(a, b, c, 0, 0, 0); }
; DI f32x16 zero16() { f32x16 z; for (int i = 0; i < 16; ++i) z[i] = 0.f; return z; }
; DI void dsa_item(const Params& P0_, int b, int item, uchar* smem) {
;     ...
;     for (int c = wave; c < nkt; c += 4) {
;       bf16x8 n0f = k0f, n1f = k1f, n2f = k2f, n3f = k3f;
;       if (c + 4 < nkt) {
;         const u16* krow = KIF + ((size_t)((tokbase >> 5) + c + 4) * 256 + lane) * 8;
;         n0f = *(const bf16x8*)(krow); n1f = *(const bf16x8*)(krow + 512); n2f = *(const bf16x8*)(krow + 1024); n3f = *(const bf16x8*)(krow + 1536);
;       }
;       f32x16 a = zero16();
;       a = mfma32(af[0], k0f, a); a = mfma32(af[1], k1f, a); a = mfma32(af[2], k2f, a); a = mfma32(af[3], k3f, a);
;       float sa = 0.f, sb = 0.f;
; #pragma unroll
;       for (int i = 0; i < 8; ++i) { sa += fmaxf(a[i], 0.f) * wa[i]; sb += fmaxf(a[8 + i], 0.f) * wb[i]; }
;       sc[h * 4096 + 32 * c + r31] = sa;
;       sc[(h + 2) * 4096 + 32 * c + r31] = sb;
;       k0f = n0f; k1f = n1f; k2f = n2f; k3f = n3f;
;     }
.Lix_go2:
	v_mfma_f32_32x32x16_bf16 v[2:17], v[30:33], v[100:103], 0
	v_mfma_f32_32x32x16_bf16 v[2:17], v[26:29], v[96:99], v[2:17]
	v_mfma_f32_32x32x16_bf16 v[2:17], v[22:25], v[92:95], v[2:17]
	v_mfma_f32_32x32x16_bf16 v[2:17], v[18:21], v[88:91], v[2:17]
	s_nop 11
	v_max_f32_e32 v10, 0, v10
	v_max_f32_e32 v2, 0, v2
	v_max_f32_e32 v11, 0, v11
	v_fma_f32 v10, v10, v75, 0
	v_max_f32_e32 v3, 0, v3
	v_max_f32_e32 v12, 0, v12
	v_fma_f32 v2, v2, v0, 0
	v_fmac_f32_e32 v10, v11, v76
	v_max_f32_e32 v4, 0, v4
	v_max_f32_e32 v13, 0, v13
	v_fmac_f32_e32 v2, v3, v68
	v_fmac_f32_e32 v10, v12, v77
	v_max_f32_e32 v5, 0, v5
	v_max_f32_e32 v14, 0, v14
	v_fmac_f32_e32 v2, v4, v69
	v_fmac_f32_e32 v10, v13, v78
	v_max_f32_e32 v6, 0, v6
	v_fmac_f32_e32 v2, v5, v70
	v_fmac_f32_e32 v10, v14, v79
	v_max_f32_e32 v3, 0, v15
	v_max_f32_e32 v7, 0, v7
	v_fmac_f32_e32 v2, v6, v71
	v_fmac_f32_e32 v10, v3, v80
	v_fmac_f32_e32 v2, v7, v72
	v_max_f32_e32 v3, 0, v8
	v_fmac_f32_e32 v2, v3, v73
	v_max_f32_e32 v3, 0, v16
	v_fmac_f32_e32 v10, v3, v81
	v_max_f32_e32 v3, 0, v9
	v_fmac_f32_e32 v2, v3, v74
	v_max_f32_e32 v3, 0, v17
	v_fmac_f32_e32 v10, v3, v82
	ds_write2st64_b32 v65, v2, v10 offset1:128
	v_add_u32_e32 v65, 0x200, v65
	s_add_i32 s32, s32, 4
	s_cmp_gt_i32 s32, s13
	s_cbranch_scc1 .LBB0_271
.Lix_v3:
	s_add_i32 s100, s32, 12
	s_cmp_le_i32 s100, s13
	s_cbranch_scc0 .Lix_ni3
	global_load_dwordx4 v[100:103], v[66:67], off offset:-2048
	global_load_dwordx4 v[96:99], v[66:67], off offset:-1024
	global_load_dwordx4 v[92:95], v[66:67], off
	global_load_dwordx4 v[88:91], v[66:67], off offset:1024

; DI f32x16 mfma32(bf16x8 a, bf16x8 b, f32x16 c) { return __builtin_amdgcn_mfma_f32_32x32x16_bf16(a, b, c, 0, 0, 0); }
; DI f32x16 zero16() { f32x16 z; for (int i = 0; i < 16; ++i) z[i] = 0.f; return z; }
; DI void dsa_item(const Params& P0_, int b, int item, uchar* smem) {
;     ...
;     for (int c = wave; c < nkt; c += 4) {
;       bf16x8 n0f = k0f, n1f = k1f, n2f = k2f, n3f = k3f;
;       if (c + 4 < nkt) {
;         const u16* krow = KIF + ((size_t)((tokbase >> 5) + c + 4) * 256 + lane) * 8;
;         n0f = *(const bf16x8*)(krow); n1f = *(const bf16x8*)(krow + 512); n2f = *(const bf16x8*)(krow + 1024); n3f = *(const bf16x8*)(krow + 1536);
;       }
;       f32x16 a = zero16();
;       a = mfma32(af[0], k0f, a); a = mfma32(af[1], k1f, a); a = mfma32(af[2], k2f, a); a = mfma32(af[3], k3f, a);
;       float sa = 0.f, sb = 0.f;
; #pragma unroll
;       for (int i = 0; i < 8; ++i) { sa += fmaxf(a[i], 0.f) * wa[i]; sb += fmaxf(a[8 + i], 0.f) * wb[i]; }
;       sc[h * 4096 + 32 * c + r31] = sa;
;       sc[(h + 2) * 4096 + 32 * c + r31] = sb;
;       k0f = n0f; k1f = n1f; k2f = n2f; k3f = n3f;
;     }
.Lix_go3:
	v_mfma_f32_32x32x16_bf16 v[2:17], v[30:33], v[116:119], 0
	v_mfma_f32_32x32x16_bf16 v[2:17], v[26:29], v[112:115], v[2:17]
	v_mfma_f32_32x32x16_bf16 v[2:17], v[22:25], v[108:111], v[2:17]
	v_mfma_f32_32x32x16_bf16 v[2:17], v[18:21], v[104:107], v[2:17]
	s_nop 11
	v_max_f32_e32 v10, 0, v10
	v_max_f32_e32 v2, 0, v2
	v_max_f32_e32 v11, 0, v11
	v_fma_f32 v10, v10, v75, 0
	v_max_f32_e32 v3, 0, v3
	v_max_f32_e32 v12, 0, v12
	v_fma_f32 v2, v2, v0, 0
	v_fmac_f32_e32 v10, v11, v76
	v_max_f32_e32 v4, 0, v4
	v_max_f32_e32 v13, 0, v13
	v_fmac_f32_e32 v2, v3, v68
	v_fmac_f32_e32 v10, v12, v77
	v_max_f32_e32 v5, 0, v5
	v_max_f32_e32 v14, 0, v14
	v_fmac_f32_e32 v2, v4, v69
	v_fmac_f32_e32 v10, v13, v78
	v_max_f32_e32 v6, 0, v6
	v_fmac_f32_e32 v2, v5, v70
	v_fmac_f32_e32 v10, v14, v79
	v_max_f32_e32 v3, 0, v15
	v_max_f32_e32 v7, 0, v7
	v_fmac_f32_e32 v2, v6, v71
	v_fmac_f32_e32 v10, v3, v80
	v_fmac_f32_e32 v2, v7, v72
	v_max_f32_e32 v3, 0, v8
	v_fmac_f32_e32 v2, v3, v73
	v_max_f32_e32 v3, 0, v16
	v_fmac_f32_e32 v10, v3, v81
	v_max_f32_e32 v3, 0, v9
	v_fmac_f32_e32 v2, v3, v74
	v_max_f32_e32 v3, 0, v17
	v_fmac_f32_e32 v10, v3, v82
	ds_write2st64_b32 v65, v2, v10 offset1:128
	v_add_u32_e32 v65, 0x200, v65
	s_add_i32 s32, s32, 4
	s_cmp_gt_i32 s32, s13
	s_cbranch_scc1 .LBB0_271
	s_branch .Lix_v0
